# cache policy: norm2 reads the just-written out-proj output (ybuf) with default-policy loads instead of non-temporal ones
# baseline (speedup 1.0000x reference)
.LBB0_116:
	global_load_dwordx4 v[68:71], v[66:67], off offset:-3072 nt
	global_load_dwordx4 v[72:75], v[66:67], off offset:-2048 nt
	global_load_dwordx4 v[88:91], v[66:67], off offset:-1024 nt
	global_load_dwordx4 v[92:95], v[66:67], off nt
	global_load_dwordx2 v[96:97], v[64:65], off
	global_load_dwordx2 v[98:99], v[64:65], off offset:512
	global_load_dwordx2 v[100:101], v[64:65], off offset:1024
	global_load_dwordx2 v[102:103], v[64:65], off offset:1536
	v_add_co_u32_e32 v122, vcc, 0xec800000, v64
	v_add_u32_e32 v86, 32, v86
	s_nop 0
	v_addc_co_u32_e32 v123, vcc, -1, v65, vcc
	v_lshl_add_u64 v[66:67], v[66:67], 0, s[6:7]
	v_lshl_add_u64 v[64:65], v[64:65], 0, s[2:3]
	v_cmp_lt_i32_e64 s[12:13], v86, v77
	s_nop 1
	s_and_b64 vcc, exec, s[12:13]
	s_cbranch_vccz .Lnrm1_nonext_first
	global_load_dwordx4 v[140:143], v[66:67], off offset:-3072 nt
	global_load_dwordx4 v[144:147], v[66:67], off offset:-2048 nt
	global_load_dwordx4 v[148:151], v[66:67], off offset:-1024 nt
	global_load_dwordx4 v[152:155], v[66:67], off nt
	global_load_dwordx2 v[156:157], v[64:65], off
	global_load_dwordx2 v[158:159], v[64:65], off offset:512
	global_load_dwordx2 v[160:161], v[64:65], off offset:1024
	global_load_dwordx2 v[162:163], v[64:65], off offset:1536
	s_waitcnt vmcnt(8)
	s_branch .Lnrm1_go_first

.Lnrm1_loop:
	v_add_co_u32_e32 v122, vcc, 0xec800000, v64
	v_add_u32_e32 v86, 32, v86
	s_nop 0
	v_addc_co_u32_e32 v123, vcc, -1, v65, vcc
	v_lshl_add_u64 v[66:67], v[66:67], 0, s[6:7]
	v_lshl_add_u64 v[64:65], v[64:65], 0, s[2:3]
	v_cmp_lt_i32_e64 s[12:13], v86, v77
	s_nop 1
	s_and_b64 vcc, exec, s[12:13]
	s_cbranch_vccz .Lnrm1_nonext_a
	global_load_dwordx4 v[140:143], v[66:67], off offset:-3072 nt
	global_load_dwordx4 v[144:147], v[66:67], off offset:-2048 nt
	global_load_dwordx4 v[148:151], v[66:67], off offset:-1024 nt
	global_load_dwordx4 v[152:155], v[66:67], off nt
	global_load_dwordx2 v[156:157], v[64:65], off
	global_load_dwordx2 v[158:159], v[64:65], off offset:512
	global_load_dwordx2 v[160:161], v[64:65], off offset:1024
	global_load_dwordx2 v[162:163], v[64:65], off offset:1536
	s_waitcnt vmcnt(12)
	s_branch .Lnrm1_go_a

.Lnrm1_go_a:
	v_lshlrev_b32_e32 v106, 16, v96
	v_and_b32_e32 v107, 0xffff0000, v96
	v_lshlrev_b32_e32 v108, 16, v97
	v_and_b32_e32 v109, 0xffff0000, v97
	v_pk_fma_f32 v[68:69], v[44:45], v[106:107], v[68:69]
	v_pk_fma_f32 v[70:71], v[46:47], v[108:109], v[70:71]
	v_lshlrev_b32_e32 v106, 16, v98
	v_and_b32_e32 v107, 0xffff0000, v98
	v_lshlrev_b32_e32 v108, 16, v99
	v_and_b32_e32 v109, 0xffff0000, v99
	v_pk_fma_f32 v[72:73], v[40:41], v[106:107], v[72:73]
	v_pk_fma_f32 v[74:75], v[42:43], v[108:109], v[74:75]
	v_lshlrev_b32_e32 v106, 16, v100
	v_and_b32_e32 v107, 0xffff0000, v100
	v_lshlrev_b32_e32 v108, 16, v101
	v_and_b32_e32 v109, 0xffff0000, v101
	v_pk_fma_f32 v[88:89], v[36:37], v[106:107], v[88:89]
	v_pk_fma_f32 v[90:91], v[38:39], v[108:109], v[90:91]
	v_lshlrev_b32_e32 v106, 16, v102
	v_and_b32_e32 v107, 0xffff0000, v102
	v_lshlrev_b32_e32 v108, 16, v103
	v_and_b32_e32 v109, 0xffff0000, v103
	v_pk_fma_f32 v[92:93], v[32:33], v[106:107], v[92:93]
	v_pk_fma_f32 v[94:95], v[34:35], v[108:109], v[94:95]
	v_mul_f32_e32 v111, v69, v69
	v_fma_f32 v110, v68, v68, v111
	v_mul_f32_e32 v111, v71, v71
	v_fma_f32 v111, v70, v70, v111
	v_add_f32_e32 v112, v110, v111
	v_mul_f32_e32 v111, v73, v73
	v_fma_f32 v110, v72, v72, v111
	v_mul_f32_e32 v111, v75, v75
	v_fma_f32 v111, v74, v74, v111
	v_add_f32_e32 v113, v110, v111
	v_mul_f32_e32 v111, v89, v89
	v_fma_f32 v110, v88, v88, v111
	v_mul_f32_e32 v111, v91, v91
	v_fma_f32 v111, v90, v90, v111
	v_add_f32_e32 v114, v110, v111
	v_mul_f32_e32 v110, v92, v92
	v_mul_f32_e32 v111, v93, v93
	v_add_f32_e32 v110, v110, v111
	v_mul_f32_e32 v111, v94, v94
	v_mul_f32_e32 v115, v95, v95
	v_add_f32_e32 v111, v111, v115
	v_add_f32_e32 v115, v110, v111
	v_add_f32_e32 v112, v112, v113
	v_add_f32_e32 v112, v112, v114
	v_add_f32_e32 v112, v112, v115
	ds_bpermute_b32 v124, v80, v112
	s_waitcnt lgkmcnt(0)
	v_add_f32_e32 v112, v112, v124
	ds_bpermute_b32 v124, v81, v112
	s_waitcnt lgkmcnt(0)
	v_add_f32_e32 v112, v112, v124
	ds_bpermute_b32 v124, v82, v112
	s_waitcnt lgkmcnt(0)
	v_add_f32_e32 v112, v112, v124
	ds_bpermute_b32 v124, v83, v112
	s_waitcnt lgkmcnt(0)
	v_add_f32_e32 v112, v112, v124
	ds_bpermute_b32 v124, v84, v112
	s_waitcnt lgkmcnt(0)
	v_add_f32_e32 v112, v112, v124
	ds_bpermute_b32 v124, v85, v112
	s_waitcnt lgkmcnt(0)
	v_add_f32_e32 v112, v112, v124
	v_fmamk_f32 v112, v112, 0x3a800000, v201
	v_cmp_gt_f32_e32 vcc, s16, v112
	v_mul_f32_e32 v124, 0x4b800000, v112
	s_nop 0
	v_cndmask_b32_e32 v112, v112, v124, vcc
	v_rsq_f32_e32 v116, v112
	s_nop 0
	v_mul_f32_e32 v124, 0x45800000, v116
	v_cndmask_b32_e32 v116, v116, v124, vcc
	v_pk_mul_f32 v[106:107], v[68:69], v[116:117] op_sel_hi:[1,0]
	v_pk_mul_f32 v[108:109], v[70:71], v[116:117] op_sel_hi:[1,0]
	v_pk_mul_f32 v[106:107], v[0:1], v[106:107]
	v_pk_mul_f32 v[108:109], v[2:3], v[108:109]
	v_pk_fma_f32 v[106:107], v[50:51], v[106:107], v[16:17]
	v_pk_fma_f32 v[108:109], v[48:49], v[108:109], v[18:19]
	v_cvt_pk_bf16_f32 v120, v106, v107
	v_cvt_pk_bf16_f32 v121, v108, v109
	global_store_dwordx2 v[122:123], v[120:121], off
	v_pk_mul_f32 v[106:107], v[72:73], v[116:117] op_sel_hi:[1,0]
	v_pk_mul_f32 v[108:109], v[74:75], v[116:117] op_sel_hi:[1,0]
	v_pk_mul_f32 v[106:107], v[4:5], v[106:107]
	v_pk_mul_f32 v[108:109], v[6:7], v[108:109]
	v_pk_fma_f32 v[106:107], v[54:55], v[106:107], v[20:21]
	v_pk_fma_f32 v[108:109], v[52:53], v[108:109], v[22:23]
	v_cvt_pk_bf16_f32 v118, v106, v107
	v_cvt_pk_bf16_f32 v119, v108, v109
	global_store_dwordx2 v[122:123], v[118:119], off offset:512
	v_pk_mul_f32 v[106:107], v[88:89], v[116:117] op_sel_hi:[1,0]
	v_pk_mul_f32 v[108:109], v[90:91], v[116:117] op_sel_hi:[1,0]
	v_pk_mul_f32 v[106:107], v[8:9], v[106:107]
	v_pk_mul_f32 v[108:109], v[10:11], v[108:109]
	v_pk_fma_f32 v[106:107], v[58:59], v[106:107], v[24:25]
	v_pk_fma_f32 v[108:109], v[56:57], v[108:109], v[26:27]
	v_cvt_pk_bf16_f32 v120, v106, v107
	v_cvt_pk_bf16_f32 v121, v108, v109
	global_store_dwordx2 v[122:123], v[120:121], off offset:1024
	v_pk_mul_f32 v[106:107], v[92:93], v[116:117] op_sel_hi:[1,0]
	v_pk_mul_f32 v[108:109], v[94:95], v[116:117] op_sel_hi:[1,0]
	v_pk_mul_f32 v[106:107], v[12:13], v[106:107]
	v_pk_mul_f32 v[108:109], v[14:15], v[108:109]
	v_pk_fma_f32 v[106:107], v[62:63], v[106:107], v[28:29]
	v_pk_fma_f32 v[108:109], v[60:61], v[108:109], v[30:31]
	v_cvt_pk_bf16_f32 v118, v106, v107
	v_cvt_pk_bf16_f32 v119, v108, v109
	global_store_dwordx2 v[122:123], v[118:119], off offset:1536
	s_and_b64 vcc, exec, s[12:13]
	s_cbranch_vccz .Lnrm1_done
	v_add_co_u32_e32 v122, vcc, 0xec800000, v64
	v_add_u32_e32 v86, 32, v86
	s_nop 0
	v_addc_co_u32_e32 v123, vcc, -1, v65, vcc
	v_lshl_add_u64 v[66:67], v[66:67], 0, s[6:7]
	v_lshl_add_u64 v[64:65], v[64:65], 0, s[2:3]
	v_cmp_lt_i32_e64 s[12:13], v86, v77
	s_nop 1
	s_and_b64 vcc, exec, s[12:13]
	s_cbranch_vccz .Lnrm1_nonext_b
	global_load_dwordx4 v[68:71], v[66:67], off offset:-3072 nt
	global_load_dwordx4 v[72:75], v[66:67], off offset:-2048 nt
	global_load_dwordx4 v[88:91], v[66:67], off offset:-1024 nt
	global_load_dwordx4 v[92:95], v[66:67], off nt
	global_load_dwordx2 v[96:97], v[64:65], off
	global_load_dwordx2 v[98:99], v[64:65], off offset:512
	global_load_dwordx2 v[100:101], v[64:65], off offset:1024
	global_load_dwordx2 v[102:103], v[64:65], off offset:1536
	s_waitcnt vmcnt(12)
	s_branch .Lnrm1_go_b
